# MoBA attn list-entry waits deferred; FFN-up epilogue stores coalesced via ds_bpermute lane transpose
# speedup vs baseline: 1.0250x; 1.0101x over previous
; __device__ __forceinline__ void attend32(const unsigned char* kimg, const unsigned char* vt, const bf16x8 (&qa)[2], const bf16x8 (&qb)[2], bool mask  , int klimA, int klimB, float mc, int lane, ...
;     const int r = lane & 15, G = lane >> 4;
;     const float c = 0.125f * 1.4426950408889634f;
;     const unsigned char* kp = kimg + r * 144 + G * 16;
;     const unsigned char* vp = vt + r * 528 + G * 16;
;     const int relA = klimA - G * 4, relB = klimB - G * 4;
;     const bool mk = __builtin_amdgcn_readfirstlane((int)mask);
;     float sumA = 0.f, sumB = 0.f;
; #pragma unroll
;     for (int dt = 0; dt < 4; ++dt) { OA[dt] = (f32x4){0.f, 0.f, 0.f, 0.f}; OB[dt] = (f32x4){0.f, 0.f, 0.f, 0.f}; }
;     bf16x8 kf[2][4], vf[2][4];
; #pragma unroll
;     for (int ks = 0; ks < 2; ++ks)
; #pragma unroll
;         for (int k4 = 0; k4 < 4; ++k4) kf[ks][k4] = *(const bf16x8*)(kp + k4 * 16 * 144 + ks * 64);
;     ...
;     u32x4 q0a, q0b, q1a, q1b;
;     { const bf16_t* qr0 = Qn + ((size_t)(cur.bhn >> 6) * SEQ + t0) * 64 + Gq * 8; const bf16_t* qr1 = Qn + ((size_t)(cur.bhn >> 6) * SEQ + t1) * 64 + Gq * 8;
;       q0a = *(const u32x4*)(qr0); q0b = *(const u32x4*)(qr0 + 32); q1a = *(const u32x4*)(qr1); q1b = *(const u32x4*)(qr1 + 32); }
;     int bufsel = 0; bool fresh = true;
;     for (;;) {
;         unsigned char* kimg = lds + bufsel * 70656; unsigned char* vt = kimg + 36864;
.LBB0_774:
	s_lshl_b64 s[0:1], s[24:25], 14
	v_ashrrev_i32_e32 v167, 31, v166
	v_ashrrev_i32_e32 v163, 31, v162
	v_lshl_add_u64 v[40:41], s[0:1], 0, v[166:167]
	v_lshl_add_u64 v[42:43], s[0:1], 0, v[162:163]
	v_lshlrev_b64 v[40:41], 7, v[40:41]
	v_lshlrev_b64 v[42:43], 7, v[42:43]
	v_lshl_add_u64 v[40:41], s[62:63], 0, v[40:41]
	v_and_b32_e32 v156, 48, v36
	v_mov_b32_e32 v157, v139
	v_lshl_add_u64 v[42:43], s[62:63], 0, v[42:43]
	v_lshl_add_u64 v[40:41], v[40:41], 0, v[156:157]
	v_lshl_add_u64 v[48:49], v[42:43], 0, v[156:157]
	global_load_dwordx4 v[44:47], v[40:41], off
	s_nop 0
	global_load_dwordx4 v[40:43], v[40:41], off offset:64
	s_nop 0
	global_load_dwordx4 v[52:55], v[48:49], off
	s_nop 0
	global_load_dwordx4 v[48:51], v[48:49], off offset:64
	s_waitcnt vmcnt(0)
	s_mul_hi_i32 s0, s24, 0x2aaaaaab
	s_lshr_b32 s1, s0, 31
	s_lshr_b32 s0, s0, 1
	s_add_i32 s0, s0, s1
	s_mul_i32 s0, s0, 12
	v_max_f32_e32 v33, v33, v33
	s_sub_i32 s58, s24, s0
	v_lshrrev_b32_e32 v37, 3, v36
	s_movk_i32 s0, 0x90
	v_max_f32_e32 v32, v32, v33
	v_max_f32_e32 v33, v35, v35
	v_mul_lo_u32 v215, v37, s0
	v_ashrrev_i32_e32 v37, 5, v36
	s_movk_i32 s1, 0x210
	v_max_f32_e32 v33, v34, v33
	v_mul_f32_e32 v32, 0x42800000, v32
	v_mul_u32_u24_e32 v212, 0x90, v38
	v_mul_u32_u24_e32 v213, 0x210, v38
	v_lshlrev_b32_e32 v38, 1, v156
	v_mov_b32_e32 v39, v139
	v_mul_lo_u32 v216, v37, s1
	v_add_u32_e32 v37, 0x200, v36
	v_mul_f32_e32 v32, v32, v33
	v_lshl_add_u64 v[160:161], s[78:79], 0, v[38:39]
	v_lshrrev_b32_e32 v38, 3, v37
	v_ashrrev_i32_e32 v37, 5, v37
	v_mul_f32_e32 v163, 0x3e38aa3b, v32
	v_lshlrev_b32_e32 v32, 4, v36
	v_mul_lo_u32 v218, v37, s1
	v_add_u32_e32 v37, 0x400, v36
	v_lshl_add_u64 v[158:159], s[62:63], 0, v[156:157]
	v_and_b32_e32 v157, 0x70, v32
	v_and_b32_e32 v167, 0x1f0, v32
	v_lshrrev_b32_e32 v32, 2, v36
	v_mul_lo_u32 v217, v38, s0
	v_lshrrev_b32_e32 v38, 3, v37
	v_ashrrev_i32_e32 v37, 5, v37
	v_add_u32_e32 v36, 0x600, v36
	v_mul_lo_u32 v220, v37, s1
	v_lshrrev_b32_e32 v37, 3, v36
	v_mul_lo_u32 v219, v38, s0
	v_mul_lo_u32 v221, v37, s0
	v_readlane_b32 s0, v250, 8
	v_and_b32_e32 v214, 12, v32
	v_xor_b32_e32 v32, 0x80000000, v163
	v_ashrrev_i32_e32 v36, 5, v36
	v_add3_u32 v223, v212, v156, s0
	v_readlane_b32 s0, v250, 9
	v_mov_b32_e32 v33, v32
	v_mov_b32_e32 v34, v32
	v_mov_b32_e32 v35, v32
	v_mul_lo_u32 v222, v36, s1
	v_add3_u32 v224, v213, v156, s0
	s_mov_b32 s49, 0
	s_mov_b64 s[54:55], -1
	v_mov_b32_e32 v225, 0
	s_branch .LBB0_777

; __device__ __forceinline__ void moba_entry(const MobaItem& it, const unsigned short* lists, int s, int wave, int r, int& t, int& slot, int& klim, bool& valid) {
;     const int loc = s * 128 + wave * 16 + r;
;     if (it.g < it.nlg) { const int idx = it.g * 256 + loc; valid = idx < it.c; const unsigned e = lists[(size_t)(it.bhn >> 6) * LIST_PER_BH + list_off(it.n) + (valid ? idx : 0)]; t = (int)(e >> 2); slot = (int)(e & 3u); klim = 255; }
;     else { klim = loc; t = it.n * 256 + loc; slot = 3; valid = true; }
; }
;     ...
;         int nt0 = 0, nslot0 = 0, nklim0 = 0, nt1 = 0, nslot1 = 0, nklim1 = 0; bool nvalid0 = false, nvalid1 = false;
;         if (has_next) { moba_entry(nxt, lists, 0, wave, r, nt0, nslot0, nklim0, nvalid0); moba_entry(nxt, lists, 1, wave, r, nt1, nslot1, nklim1, nvalid1); }
.LBB0_789:
	s_andn2_b64 vcc, exec, s[24:25]
	s_mul_i32 s26, s47, 63
	s_cbranch_vccnz .LBB0_792
	s_add_i32 s24, s47, -1
	s_mul_i32 s24, s24, s47
	s_lshr_b32 s25, s24, 31
	s_add_i32 s24, s24, s25
	s_lshr_b32 s24, s24, 1
	s_sub_i32 s24, s26, s24
	s_ashr_i32 s59, s74, 6
	s_lshl_b32 s24, s24, 8
	s_ashr_i32 s25, s24, 31
	s_mul_hi_i32 s75, s59, 0xfc000
	s_mul_i32 s59, s59, 0xfc000
	v_lshl_add_u32 v36, s89, 8, v210
	s_add_u32 s59, s71, s59
	v_cmp_lt_i32_e32 vcc, v36, v38
	s_addc_u32 s75, s33, s75
	s_lshl_b64 s[24:25], s[24:25], 1
	v_cndmask_b32_e32 v36, 0, v36, vcc
	s_add_u32 s24, s59, s24
	v_ashrrev_i32_e32 v37, 31, v36
	s_addc_u32 s25, s75, s25
	v_lshl_add_u64 v[36:37], v[36:37], 1, s[24:25]
	global_load_ushort v168, v[36:37], off
	v_cndmask_b32_e64 v226, 0, 1, vcc
	v_mov_b32_e32 v228, 0xff
	s_mov_b64 s[24:25], -1
	s_and_b64 vcc, exec, s[0:1]
	s_mov_b64 s[0:1], -1
	s_cbranch_vccz .LBB0_794
	s_branch .LBB0_793

; __device__ __forceinline__ void moba_entry(const MobaItem& it, const unsigned short* lists, int s, int wave, int r, int& t, int& slot, int& klim, bool& valid) {
;     const int loc = s * 128 + wave * 16 + r;
;     if (it.g < it.nlg) { const int idx = it.g * 256 + loc; valid = idx < it.c; const unsigned e = lists[(size_t)(it.bhn >> 6) * LIST_PER_BH + list_off(it.n) + (valid ? idx : 0)]; t = (int)(e >> 2); slot = (int)(e & 3u); klim = 255; }
;     else { klim = loc; t = it.n * 256 + loc; slot = 3; valid = true; }
; }
;     ...
;         int nt0 = 0, nslot0 = 0, nklim0 = 0, nt1 = 0, nslot1 = 0, nklim1 = 0; bool nvalid0 = false, nvalid1 = false;
;         if (has_next) { moba_entry(nxt, lists, 0, wave, r, nt0, nslot0, nklim0, nvalid0); moba_entry(nxt, lists, 1, wave, r, nt1, nslot1, nklim1, nvalid1); }
.LBB0_792:
	v_mov_b32_e32 v226, 1
	v_mov_b32_e32 v227, 3
	v_lshl_or_b32 v168, v168, 2, 3
	v_mov_b32_e32 v228, v210
	s_mov_b64 s[24:25], -1
	s_and_b64 vcc, exec, s[0:1]
	s_mov_b64 s[0:1], -1
	s_cbranch_vccz .LBB0_794
.LBB0_793:
	v_lshl_add_u32 v170, s47, 8, v211
	v_lshl_or_b32 v170, v170, 2, 3
	s_mov_b64 s[0:1], 0
.LBB0_794:
	v_mov_b32_e32 v230, 3
	s_andn2_b64 vcc, exec, s[0:1]
	v_mov_b32_e32 v229, v211
	s_cbranch_vccnz .LBB0_796
	s_add_i32 s0, s47, -1
	s_mul_i32 s0, s0, s47
	s_lshr_b32 s1, s0, 31
	s_add_i32 s0, s0, s1
	s_lshr_b32 s0, s0, 1
	s_sub_i32 s0, s26, s0
	s_ashr_i32 s24, s74, 6
	s_lshl_b32 s0, s0, 8
	s_ashr_i32 s1, s0, 31
	s_mul_hi_i32 s25, s24, 0xfc000
	s_mul_i32 s24, s24, 0xfc000
	v_lshl_add_u32 v36, s89, 8, v211
	s_add_u32 s24, s71, s24
	v_cmp_lt_i32_e32 vcc, v36, v38
	s_addc_u32 s25, s33, s25
	s_lshl_b64 s[0:1], s[0:1], 1
	v_cndmask_b32_e32 v36, 0, v36, vcc
	s_add_u32 s0, s24, s0
	v_ashrrev_i32_e32 v37, 31, v36
	s_addc_u32 s1, s25, s1
	v_lshl_add_u64 v[36:37], v[36:37], 1, s[0:1]
	global_load_ushort v170, v[36:37], off
	v_mov_b32_e32 v229, 0xff
	s_orn2_b64 s[24:25], vcc, exec

.LBB0_799:
	s_waitcnt lgkmcnt(7)
	v_mfma_f32_16x16x32_bf16 v[88:91], v[120:123], v[44:47], v[32:35]
	v_mfma_f32_16x16x32_bf16 v[92:95], v[120:123], v[52:55], v[32:35]
	s_waitcnt lgkmcnt(5)
	v_mfma_f32_16x16x32_bf16 v[96:99], v[132:135], v[44:47], v[32:35]
	v_mfma_f32_16x16x32_bf16 v[100:103], v[132:135], v[52:55], v[32:35]
	s_waitcnt lgkmcnt(3)
	v_mfma_f32_16x16x32_bf16 v[120:123], v[128:131], v[44:47], v[32:35]
	v_mfma_f32_16x16x32_bf16 v[128:131], v[128:131], v[52:55], v[32:35]
	s_waitcnt lgkmcnt(1)
	v_mfma_f32_16x16x32_bf16 v[132:135], v[124:127], v[44:47], v[32:35]
	v_mfma_f32_16x16x32_bf16 v[124:127], v[124:127], v[52:55], v[32:35]
	v_mfma_f32_16x16x32_bf16 v[174:177], v[116:119], v[40:43], v[88:91]
	v_mfma_f32_16x16x32_bf16 v[178:181], v[112:115], v[40:43], v[96:99]
	v_mfma_f32_16x16x32_bf16 v[116:119], v[116:119], v[48:51], v[92:95]
	v_mfma_f32_16x16x32_bf16 v[112:115], v[112:115], v[48:51], v[100:103]
	v_mfma_f32_16x16x32_bf16 v[120:123], v[108:111], v[40:43], v[120:123]
	v_mfma_f32_16x16x32_bf16 v[108:111], v[108:111], v[48:51], v[128:131]
	s_waitcnt lgkmcnt(0)
	v_mfma_f32_16x16x32_bf16 v[128:131], v[104:107], v[40:43], v[132:135]
	v_mfma_f32_16x16x32_bf16 v[104:107], v[104:107], v[48:51], v[124:127]
	ds_read_b128 v[100:103], v171
	ds_read_b128 v[96:99], v171 offset:8448
	ds_read_b128 v[92:95], v171 offset:16896
	ds_read_b128 v[88:91], v171 offset:25344
	v_exp_f32_e32 v198, v174
	v_exp_f32_e32 v199, v116
	v_exp_f32_e32 v202, v175
	v_exp_f32_e32 v203, v117
	v_exp_f32_e32 v196, v176
	v_exp_f32_e32 v197, v118
	v_exp_f32_e32 v200, v177
	v_exp_f32_e32 v201, v119
	v_exp_f32_e32 v190, v178
	v_exp_f32_e32 v191, v112
	v_exp_f32_e32 v194, v179
	v_exp_f32_e32 v195, v113
	v_exp_f32_e32 v188, v180
	v_exp_f32_e32 v189, v114
	v_exp_f32_e32 v192, v181
	v_exp_f32_e32 v193, v115
	v_exp_f32_e32 v182, v120
	v_exp_f32_e32 v183, v108
	v_exp_f32_e32 v186, v121
	v_exp_f32_e32 v187, v109
	v_exp_f32_e32 v180, v122
	v_exp_f32_e32 v181, v110
	v_exp_f32_e32 v184, v123
	v_exp_f32_e32 v185, v111
	v_exp_f32_e32 v174, v128
	v_exp_f32_e32 v175, v104
	v_exp_f32_e32 v178, v129
	v_exp_f32_e32 v179, v105
	v_exp_f32_e32 v36, v130
	v_exp_f32_e32 v37, v106
	v_exp_f32_e32 v176, v131
	v_exp_f32_e32 v177, v107
	s_and_b64 vcc, exec, s[0:1]
	s_cbranch_vccz .LBB0_798
	v_add_u32_e32 v104, s26, v233
	v_add_u32_e32 v105, s26, v232
	v_cmp_lt_i32_e32 vcc, -1, v104
	s_nop 1
	v_cndmask_b32_e32 v198, 0, v198, vcc
	v_cmp_lt_i32_e32 vcc, -1, v105
	s_nop 1
	v_cndmask_b32_e32 v199, 0, v199, vcc
	v_cmp_lt_i32_e32 vcc, 0, v104
	s_nop 1
	v_cndmask_b32_e32 v202, 0, v202, vcc
	v_cmp_lt_i32_e32 vcc, 0, v105
	s_nop 1
	v_cndmask_b32_e32 v203, 0, v203, vcc
	v_cmp_lt_i32_e32 vcc, 1, v104
	s_nop 1
	v_cndmask_b32_e32 v196, 0, v196, vcc
	v_cmp_lt_i32_e32 vcc, 1, v105
	s_nop 1
	v_cndmask_b32_e32 v197, 0, v197, vcc
	v_cmp_lt_i32_e32 vcc, 2, v104
	s_nop 1
	v_cndmask_b32_e32 v200, 0, v200, vcc
	v_cmp_lt_i32_e32 vcc, 2, v105
	s_nop 1
	v_cndmask_b32_e32 v201, 0, v201, vcc
	v_cmp_lt_i32_e32 vcc, 15, v104
	s_nop 1
	v_cndmask_b32_e32 v190, 0, v190, vcc
	v_cmp_lt_i32_e32 vcc, 15, v105
	s_nop 1
	v_cndmask_b32_e32 v191, 0, v191, vcc
	v_cmp_lt_i32_e32 vcc, 16, v104
	s_nop 1
	v_cndmask_b32_e32 v194, 0, v194, vcc
	v_cmp_lt_i32_e32 vcc, 16, v105
	s_nop 1
	v_cndmask_b32_e32 v195, 0, v195, vcc
	v_cmp_lt_i32_e32 vcc, 17, v104
	s_nop 1
	v_cndmask_b32_e32 v188, 0, v188, vcc
	v_cmp_lt_i32_e32 vcc, 17, v105
	s_nop 1
	v_cndmask_b32_e32 v189, 0, v189, vcc
	v_cmp_lt_i32_e32 vcc, 18, v104
	s_nop 1
	v_cndmask_b32_e32 v192, 0, v192, vcc
	v_cmp_lt_i32_e32 vcc, 18, v105
	s_nop 1
	v_cndmask_b32_e32 v193, 0, v193, vcc
	v_cmp_lt_i32_e32 vcc, 31, v104
	s_nop 1
	v_cndmask_b32_e32 v182, 0, v182, vcc
	v_cmp_lt_i32_e32 vcc, 31, v105
	s_nop 1
	v_cndmask_b32_e32 v183, 0, v183, vcc
	v_cmp_lt_i32_e32 vcc, 32, v104
	s_nop 1
	v_cndmask_b32_e32 v186, 0, v186, vcc
	v_cmp_lt_i32_e32 vcc, 32, v105
	s_nop 1
	v_cndmask_b32_e32 v187, 0, v187, vcc
	v_cmp_lt_i32_e32 vcc, 33, v104
	s_nop 1
	v_cndmask_b32_e32 v180, 0, v180, vcc
	v_cmp_lt_i32_e32 vcc, 33, v105
	s_nop 1
	v_cndmask_b32_e32 v181, 0, v181, vcc
	v_cmp_lt_i32_e32 vcc, 34, v104
	s_nop 1
	v_cndmask_b32_e32 v184, 0, v184, vcc
	v_cmp_lt_i32_e32 vcc, 34, v105
	s_nop 1
	v_cndmask_b32_e32 v185, 0, v185, vcc
	v_cmp_lt_i32_e32 vcc, 47, v104
	s_nop 1
	v_cndmask_b32_e32 v174, 0, v174, vcc
	v_cmp_lt_i32_e32 vcc, 47, v105
	s_nop 1
	v_cndmask_b32_e32 v175, 0, v175, vcc
	v_cmp_lt_i32_e32 vcc, 48, v104
	s_nop 1
	v_cndmask_b32_e32 v178, 0, v178, vcc
	v_cmp_lt_i32_e32 vcc, 48, v105
	s_nop 1
	v_cndmask_b32_e32 v179, 0, v179, vcc
	v_cmp_lt_i32_e32 vcc, 49, v104
	s_nop 1
	v_cndmask_b32_e32 v36, 0, v36, vcc
	v_cmp_lt_i32_e32 vcc, 49, v105
	s_nop 1
	v_cndmask_b32_e32 v37, 0, v37, vcc
	v_cmp_lt_i32_e32 vcc, 50, v104
	s_nop 1
	v_cndmask_b32_e32 v176, 0, v176, vcc
	v_cmp_lt_i32_e32 vcc, 50, v105
	s_nop 1
	v_cndmask_b32_e32 v177, 0, v177, vcc
	s_branch .LBB0_798

; __device__ __forceinline__ void attend32(const unsigned char* kimg, const unsigned char* vt, const bf16x8 (&qa)[2], const bf16x8 (&qb)[2], bool mask  , int klimA, int klimB, float mc, int lane, ...
;     ...
;     if (pref) {
;         nq0 = *(const u32x4*)(nqbase + (size_t)nt0 * 64); nq1 = *(const u32x4*)(nqbase + (size_t)nt0 * 64 + 32);
;         nq2 = *(const u32x4*)(nqbase + (size_t)nt1 * 64); nq3 = *(const u32x4*)(nqbase + (size_t)nt1 * 64 + 32);
;     }
;     ...
;         u32x4 nqa = q0a, nqb = q0b, nqc = q1a, nqd = q1b; bool nq_done = false;
.LBB0_802:
	v_mov_b64_e32 v[102:103], v[46:47]
	v_mov_b64_e32 v[98:99], v[42:43]
	v_mov_b64_e32 v[94:95], v[54:55]
	v_mov_b64_e32 v[90:91], v[50:51]
	s_and_b64 vcc, exec, s[42:43]
	v_mov_b64_e32 v[100:101], v[44:45]
	v_mov_b64_e32 v[96:97], v[40:41]
	v_mov_b64_e32 v[92:93], v[52:53]
	v_mov_b64_e32 v[88:89], v[48:49]
	s_cbranch_vccz .LBB0_804
	s_waitcnt vmcnt(0)
	v_and_b32_e32 v227, 3, v168
	v_and_b32_e32 v230, 3, v170
	v_lshrrev_b32_e32 v168, 2, v168
	v_lshrrev_b32_e32 v170, 2, v170
	s_ashr_i32 s26, s74, 6
	s_ashr_i32 s27, s26, 31
	s_lshl_b64 s[26:27], s[26:27], 21
	v_ashrrev_i32_e32 v169, 31, v168
	v_lshl_add_u64 v[36:37], v[158:159], 0, s[26:27]
	v_lshlrev_b64 v[88:89], 7, v[168:169]
	v_ashrrev_i32_e32 v171, 31, v170
	v_lshl_add_u64 v[88:89], v[36:37], 0, v[88:89]
	v_lshlrev_b64 v[90:91], 7, v[170:171]
	v_lshl_add_u64 v[36:37], v[36:37], 0, v[90:91]
	global_load_dwordx4 v[100:103], v[88:89], off
	global_load_dwordx4 v[96:99], v[88:89], off offset:64
	global_load_dwordx4 v[92:95], v[36:37], off
	s_nop 0
	global_load_dwordx4 v[88:91], v[36:37], off offset:64

;     ...
;         if (!has_next) break;
;         if (nq_done) { q0a = nqa; q0b = nqb; q1a = nqc; q1b = nqd; }
;         else {
;             const bf16_t* qr0 = Qn + ((size_t)(nxt.bhn >> 6) * SEQ + nt0) * 64 + Gq * 8; const bf16_t* qr1 = Qn + ((size_t)(nxt.bhn >> 6) * SEQ + nt1) * 64 + Gq * 8;
;             q0a = *(const u32x4*)(qr0); q0b = *(const u32x4*)(qr0 + 32); q1a = *(const u32x4*)(qr1); q1b = *(const u32x4*)(qr1 + 32);
;         }
.LBB0_813:
	s_xor_b64 s[0:1], s[42:43], -1
	s_andn2_b64 vcc, exec, s[0:1]
	s_cbranch_vccnz .LBB0_775
	s_waitcnt vmcnt(0)
	v_and_b32_e32 v227, 3, v168
	v_and_b32_e32 v230, 3, v170
	v_lshrrev_b32_e32 v168, 2, v168
	v_lshrrev_b32_e32 v170, 2, v170
	s_ashr_i32 s0, s74, 6
	s_ashr_i32 s1, s0, 31
	s_lshl_b64 s[0:1], s[0:1], 14
	v_ashrrev_i32_e32 v171, 31, v170
	v_ashrrev_i32_e32 v169, 31, v168
	v_lshl_add_u64 v[40:41], s[0:1], 0, v[170:171]
	v_lshl_add_u64 v[36:37], s[0:1], 0, v[168:169]
	v_lshlrev_b64 v[40:41], 7, v[40:41]
	v_lshlrev_b64 v[36:37], 7, v[36:37]
	v_lshl_add_u64 v[40:41], v[158:159], 0, v[40:41]
	v_lshl_add_u64 v[36:37], v[158:159], 0, v[36:37]
	global_load_dwordx4 v[88:91], v[40:41], off offset:64
	global_load_dwordx4 v[92:95], v[40:41], off
	global_load_dwordx4 v[96:99], v[36:37], off offset:64
	global_load_dwordx4 v[100:103], v[36:37], off
	s_branch .LBB0_775

; __device__ __forceinline__ unsigned cvt_pk_bf16(float lo, float hi) { unsigned r; asm volatile("v_cvt_pk_bf16_f32 %0, %1, %2" : "=v"(r) : "v"(lo), "v"(hi)); return r; }
;     __device__ __forceinline__ void operator()(const f32x4 (&acc)[2][2][4][2], const Unit& u, int wr, int wc, int fr, int fq) const {
;     ...
;                 const int row = row0 + ai * HALF + m * 16;
;                 const f32x4* sp = (const f32x4*)(ss + (size_t)row * 16);
;                 const f32x4 a0 = sp[0], a1 = sp[1], a2 = sp[2], a3 = sp[3];
;                 const float tot = ((a0.x + a0.y) + (a0.z + a0.w)) + ((a1.x + a1.y) + (a1.z + a1.w)) + ((a2.x + a2.y) + (a2.z + a2.w)) + ((a3.x + a3.y) + (a3.z + a3.w));
;                 const float rs = rsqrtf(tot * (1.0f / 1024.0f) + 1e-6f);
;                 bf16_t* rowp = O + (size_t)row * ldc + col0;
; #pragma unroll
;                 for (int bj = 0; bj < 2; ++bj) {
;                     f32x4 v0 = acc[ai][bj][m][0] * rs, v1 = acc[ai][bj][m][1] * rs;
;                     if (ACT == 1) {
; #pragma unroll
;                         for (int e = 0; e < 4; ++e) { float a = fmaxf(v0[e], 0.f); v0[e] = a * a; float b = fmaxf(v1[e], 0.f); v1[e] = b * b; }
;                     }
;                     u32x4 w; w.x = cvt_pk_bf16(v0[0], v0[1]); w.y = cvt_pk_bf16(v0[2], v0[3]); w.z = cvt_pk_bf16(v1[0], v1[1]); w.w = cvt_pk_bf16(v1[2], v1[3]);
;                     *(u32x4*)(rowp + bj * HALF) = w;
.LBB0_1155:
	v_lshl_add_u32 v152, s88, 8, v154
	v_ashrrev_i32_e32 v153, 31, v152
	v_lshlrev_b64 v[176:177], 6, v[152:153]
	v_and_or_b32 v176, v204, 48, v176
	v_lshl_add_u64 v[176:177], s[90:91], 0, v[176:177]
	v_mov_b32_e32 v178, 0x2000
	v_mov_b32_e32 v179, 0
	v_lshl_add_u64 v[178:179], v[176:177], 0, v[178:179]
	global_load_dwordx4 v[180:183], v[176:177], off
	global_load_dwordx4 v[184:187], v[176:177], off offset:1024
	global_load_dwordx4 v[188:191], v[176:177], off offset:2048
	global_load_dwordx4 v[192:195], v[176:177], off offset:3072
	global_load_dwordx4 v[196:199], v[178:179], off
	global_load_dwordx4 v[208:211], v[178:179], off offset:1024
	global_load_dwordx4 v[212:215], v[178:179], off offset:2048
	global_load_dwordx4 v[216:219], v[178:179], off offset:3072
	v_bfe_u32 v228, v204, 2, 4
	v_and_b32_e32 v229, -16, v154
	v_or_b32_e32 v229, v229, v228
	v_lshl_add_u32 v152, s88, 8, v229
	v_ashrrev_i32_e32 v153, 31, v152
	v_and_b32_e32 v229, 3, v204
	v_lshlrev_b32_e32 v230, 3, v229
	v_and_b32_e32 v231, -32, v156
	v_or_b32_e32 v230, v230, v231
	v_lshl_add_u32 v228, v229, 4, v228
	v_lshlrev_b32_e32 v228, 2, v228
	v_lshl_or_b32 v150, s30, 8, v230
	v_ashrrev_i32_e32 v151, 31, v150
	v_lshlrev_b64 v[150:151], 1, v[150:151]
	s_mov_b64 s[24:25], -1
	v_lshlrev_b64 v[160:161], 13, v[152:153]
	v_lshl_add_u64 v[160:161], s[78:79], 0, v[160:161]
	v_lshl_add_u64 v[160:161], v[160:161], 0, v[150:151]
	s_waitcnt vmcnt(0)
	v_add_f32_e32 v180, v180, v181
	v_add_f32_e32 v182, v182, v183
	v_add_f32_e32 v184, v184, v185
	v_add_f32_e32 v186, v186, v187
	v_add_f32_e32 v188, v188, v189
	v_add_f32_e32 v190, v190, v191
	v_add_f32_e32 v192, v192, v193
	v_add_f32_e32 v194, v194, v195
	v_add_f32_e32 v196, v196, v197
	v_add_f32_e32 v198, v198, v199
	v_add_f32_e32 v208, v208, v209
	v_add_f32_e32 v210, v210, v211
	v_add_f32_e32 v212, v212, v213
	v_add_f32_e32 v214, v214, v215
	v_add_f32_e32 v216, v216, v217
	v_add_f32_e32 v218, v218, v219
	v_add_f32_e32 v180, v180, v182
	v_add_f32_e32 v184, v184, v186
	v_add_f32_e32 v188, v188, v190
	v_add_f32_e32 v192, v192, v194
	v_add_f32_e32 v196, v196, v198
	v_add_f32_e32 v208, v208, v210
	v_add_f32_e32 v212, v212, v214
	v_add_f32_e32 v216, v216, v218
	v_mov_b32_e32 v181, v180
	v_mov_b32_e32 v185, v184
	v_mov_b32_e32 v189, v188
	v_mov_b32_e32 v193, v192
	v_mov_b32_e32 v197, v196
	v_mov_b32_e32 v209, v208
	v_mov_b32_e32 v213, v212
	v_mov_b32_e32 v217, v216
	s_nop 1
	v_permlane16_swap_b32_e32 v180, v181
	v_permlane16_swap_b32_e32 v184, v185
	v_permlane16_swap_b32_e32 v188, v189
	v_permlane16_swap_b32_e32 v192, v193
	v_permlane16_swap_b32_e32 v196, v197
	v_permlane16_swap_b32_e32 v208, v209
	v_permlane16_swap_b32_e32 v212, v213
	v_permlane16_swap_b32_e32 v216, v217
	v_add_f32_e32 v180, v180, v181
	v_add_f32_e32 v184, v184, v185
	v_add_f32_e32 v188, v188, v189
	v_add_f32_e32 v192, v192, v193
	v_add_f32_e32 v196, v196, v197
	v_add_f32_e32 v208, v208, v209
	v_add_f32_e32 v212, v212, v213
	v_add_f32_e32 v216, v216, v217
	v_mov_b32_e32 v181, v180
	v_mov_b32_e32 v185, v184
	v_mov_b32_e32 v189, v188
	v_mov_b32_e32 v193, v192
	v_mov_b32_e32 v197, v196
	v_mov_b32_e32 v209, v208
	v_mov_b32_e32 v213, v212
	v_mov_b32_e32 v217, v216
	s_nop 1
	v_permlane32_swap_b32_e32 v180, v181
	v_permlane32_swap_b32_e32 v184, v185
	v_permlane32_swap_b32_e32 v188, v189
	v_permlane32_swap_b32_e32 v192, v193
	v_permlane32_swap_b32_e32 v196, v197
	v_permlane32_swap_b32_e32 v208, v209
	v_permlane32_swap_b32_e32 v212, v213
	v_permlane32_swap_b32_e32 v216, v217
	v_add_f32_e32 v180, v180, v181
	v_add_f32_e32 v184, v184, v185
	v_add_f32_e32 v188, v188, v189
	v_add_f32_e32 v192, v192, v193
	v_add_f32_e32 v196, v196, v197
	v_add_f32_e32 v208, v208, v209
	v_add_f32_e32 v212, v212, v213
	v_add_f32_e32 v216, v216, v217
	v_fmamk_f32 v180, v180, 0x3a800000, v137
	v_cmp_gt_f32_e32 vcc, s4, v180
	v_mul_f32_e32 v181, 0x4b800000, v180
	s_nop 0
	v_cndmask_b32_e32 v180, v180, v181, vcc
	v_rsq_f32_e32 v180, v180
	s_nop 0
	v_mul_f32_e32 v181, 0x45800000, v180
	v_cndmask_b32_e32 v180, v180, v181, vcc
	v_fmamk_f32 v184, v184, 0x3a800000, v137
	v_cmp_gt_f32_e32 vcc, s4, v184
	v_mul_f32_e32 v185, 0x4b800000, v184
	s_nop 0
	v_cndmask_b32_e32 v184, v184, v185, vcc
	v_rsq_f32_e32 v184, v184
	s_nop 0
	v_mul_f32_e32 v185, 0x45800000, v184
	v_cndmask_b32_e32 v184, v184, v185, vcc
	v_fmamk_f32 v188, v188, 0x3a800000, v137
	v_cmp_gt_f32_e32 vcc, s4, v188
	v_mul_f32_e32 v189, 0x4b800000, v188
	s_nop 0
	v_cndmask_b32_e32 v188, v188, v189, vcc
	v_rsq_f32_e32 v188, v188
	s_nop 0
	v_mul_f32_e32 v189, 0x45800000, v188
	v_cndmask_b32_e32 v188, v188, v189, vcc
	v_fmamk_f32 v192, v192, 0x3a800000, v137
	v_cmp_gt_f32_e32 vcc, s4, v192
	v_mul_f32_e32 v193, 0x4b800000, v192
	s_nop 0
	v_cndmask_b32_e32 v192, v192, v193, vcc
	v_rsq_f32_e32 v192, v192
	s_nop 0
	v_mul_f32_e32 v193, 0x45800000, v192
	v_cndmask_b32_e32 v192, v192, v193, vcc
	v_fmamk_f32 v196, v196, 0x3a800000, v137
	v_cmp_gt_f32_e32 vcc, s4, v196
	v_mul_f32_e32 v197, 0x4b800000, v196
	s_nop 0
	v_cndmask_b32_e32 v196, v196, v197, vcc
	v_rsq_f32_e32 v196, v196
	s_nop 0
	v_mul_f32_e32 v197, 0x45800000, v196
	v_cndmask_b32_e32 v196, v196, v197, vcc
	v_fmamk_f32 v208, v208, 0x3a800000, v137
	v_cmp_gt_f32_e32 vcc, s4, v208
	v_mul_f32_e32 v209, 0x4b800000, v208
	s_nop 0
	v_cndmask_b32_e32 v208, v208, v209, vcc
	v_rsq_f32_e32 v208, v208
	s_nop 0
	v_mul_f32_e32 v209, 0x45800000, v208
	v_cndmask_b32_e32 v208, v208, v209, vcc
	v_fmamk_f32 v212, v212, 0x3a800000, v137
	v_cmp_gt_f32_e32 vcc, s4, v212
	v_mul_f32_e32 v213, 0x4b800000, v212
	s_nop 0
	v_cndmask_b32_e32 v212, v212, v213, vcc
	v_rsq_f32_e32 v212, v212
	s_nop 0
	v_mul_f32_e32 v213, 0x45800000, v212
; __device__ __forceinline__ unsigned cvt_pk_bf16(float lo, float hi) { unsigned r; asm volatile("v_cvt_pk_bf16_f32 %0, %1, %2" : "=v"(r) : "v"(lo), "v"(hi)); return r; }
;     __device__ __forceinline__ void operator()(const f32x4 (&acc)[2][2][4][2], const Unit& u, int wr, int wc, int fr, int fq) const {
;     ...
;                 const int row = row0 + ai * HALF + m * 16;
;                 const f32x4* sp = (const f32x4*)(ss + (size_t)row * 16);
;                 const f32x4 a0 = sp[0], a1 = sp[1], a2 = sp[2], a3 = sp[3];
;                 const float tot = ((a0.x + a0.y) + (a0.z + a0.w)) + ((a1.x + a1.y) + (a1.z + a1.w)) + ((a2.x + a2.y) + (a2.z + a2.w)) + ((a3.x + a3.y) + (a3.z + a3.w));
;                 const float rs = rsqrtf(tot * (1.0f / 1024.0f) + 1e-6f);
;                 bf16_t* rowp = O + (size_t)row * ldc + col0;
; #pragma unroll
;                 for (int bj = 0; bj < 2; ++bj) {
;                     f32x4 v0 = acc[ai][bj][m][0] * rs, v1 = acc[ai][bj][m][1] * rs;
;                     if (ACT == 1) {
; #pragma unroll
;                         for (int e = 0; e < 4; ++e) { float a = fmaxf(v0[e], 0.f); v0[e] = a * a; float b = fmaxf(v1[e], 0.f); v1[e] = b * b; }
;                     }
;                     u32x4 w; w.x = cvt_pk_bf16(v0[0], v0[1]); w.y = cvt_pk_bf16(v0[2], v0[3]); w.z = cvt_pk_bf16(v1[0], v1[1]); w.w = cvt_pk_bf16(v1[2], v1[3]);
;                     *(u32x4*)(rowp + bj * HALF) = w;
	v_cndmask_b32_e32 v212, v212, v213, vcc
	v_fmamk_f32 v216, v216, 0x3a800000, v137
	v_cmp_gt_f32_e32 vcc, s4, v216
	v_mul_f32_e32 v217, 0x4b800000, v216
	s_nop 0
	v_cndmask_b32_e32 v216, v216, v217, vcc
	v_rsq_f32_e32 v216, v216
	s_nop 0
	v_mul_f32_e32 v217, 0x45800000, v216
	v_cndmask_b32_e32 v216, v216, v217, vcc
	v_mov_b32_e32 v158, v180
	v_pk_mul_f32 v[120:121], v[120:121], v[158:159] op_sel_hi:[1,0]
	v_pk_mul_f32 v[124:125], v[124:125], v[158:159] op_sel_hi:[1,0]
	v_pk_mul_f32 v[122:123], v[122:123], v[158:159] op_sel_hi:[1,0]
	v_max_f32_e32 v120, 0, v120
	v_pk_mul_f32 v[126:127], v[126:127], v[158:159] op_sel_hi:[1,0]
	v_mul_f32_e32 v153, v120, v120
	v_max_f32_e32 v120, 0, v125
	v_max_f32_e32 v121, 0, v121
	v_max_f32_e32 v122, 0, v122
	v_max_f32_e32 v124, 0, v124
	v_mul_f32_e32 v120, v120, v120
	v_mul_f32_e32 v125, v121, v121
	v_max_f32_e32 v121, 0, v126
	v_mul_f32_e32 v126, v122, v122
	v_max_f32_e32 v122, 0, v127
	v_max_f32_e32 v123, 0, v123
	v_pk_mul_f32 v[112:113], v[112:113], v[158:159] op_sel_hi:[1,0]
	v_mul_f32_e32 v124, v124, v124
	v_mul_f32_e32 v121, v121, v121
	v_mul_f32_e32 v122, v122, v122
	v_mul_f32_e32 v123, v123, v123
	v_cvt_pk_bf16_f32 v120, v124, v120
	v_pk_mul_f32 v[116:117], v[116:117], v[158:159] op_sel_hi:[1,0]
	v_pk_mul_f32 v[114:115], v[114:115], v[158:159] op_sel_hi:[1,0]
	v_max_f32_e32 v112, 0, v112
	v_cvt_pk_bf16_f32 v121, v121, v122
	v_cvt_pk_bf16_f32 v122, v153, v125
	v_cvt_pk_bf16_f32 v123, v126, v123
	ds_bpermute_b32 v220, v228, v120
	ds_bpermute_b32 v221, v228, v121
	ds_bpermute_b32 v222, v228, v122
	ds_bpermute_b32 v223, v228, v123
	v_pk_mul_f32 v[118:119], v[118:119], v[158:159] op_sel_hi:[1,0]
	v_max_f32_e32 v113, 0, v113
	v_mul_f32_e32 v120, v112, v112
	v_max_f32_e32 v112, 0, v117
	v_max_f32_e32 v114, 0, v114
	v_max_f32_e32 v116, 0, v116
	v_mul_f32_e32 v112, v112, v112
	v_mul_f32_e32 v117, v113, v113
	v_max_f32_e32 v113, 0, v118
	v_mul_f32_e32 v118, v114, v114
	v_max_f32_e32 v114, 0, v119
	v_max_f32_e32 v115, 0, v115
	v_mul_f32_e32 v116, v116, v116
	v_mul_f32_e32 v113, v113, v113
	v_mul_f32_e32 v114, v114, v114
	v_mul_f32_e32 v115, v115, v115
	v_cvt_pk_bf16_f32 v112, v116, v112
	v_cvt_pk_bf16_f32 v113, v113, v114
	v_cvt_pk_bf16_f32 v114, v120, v117
	v_cvt_pk_bf16_f32 v115, v118, v115
	ds_bpermute_b32 v224, v228, v112
	ds_bpermute_b32 v225, v228, v113
	ds_bpermute_b32 v226, v228, v114
	ds_bpermute_b32 v227, v228, v115
	s_waitcnt lgkmcnt(4)
	global_store_dwordx4 v[160:161], v[220:223], off
	s_waitcnt lgkmcnt(0)
	global_store_dwordx4 v[160:161], v[224:227], off offset:256
	s_nop 1
	v_or_b32_e32 v112, 16, v152
	v_ashrrev_i32_e32 v113, 31, v112
	v_lshlrev_b64 v[112:113], 13, v[112:113]
	v_lshl_add_u64 v[112:113], s[78:79], 0, v[112:113]
	v_lshl_add_u64 v[112:113], v[112:113], 0, v[150:151]
	v_mov_b32_e32 v114, v184
	v_pk_mul_f32 v[104:105], v[104:105], v[114:115] op_sel_hi:[1,0]
	v_pk_mul_f32 v[108:109], v[108:109], v[114:115] op_sel_hi:[1,0]
	v_pk_mul_f32 v[106:107], v[106:107], v[114:115] op_sel_hi:[1,0]
	v_max_f32_e32 v104, 0, v104
	v_pk_mul_f32 v[110:111], v[110:111], v[114:115] op_sel_hi:[1,0]
	v_mul_f32_e32 v115, v104, v104
	v_max_f32_e32 v104, 0, v109
	v_max_f32_e32 v105, 0, v105
	v_max_f32_e32 v106, 0, v106
	v_max_f32_e32 v108, 0, v108
	v_mul_f32_e32 v104, v104, v104
	v_mul_f32_e32 v109, v105, v105
	v_max_f32_e32 v105, 0, v110
	v_mul_f32_e32 v110, v106, v106
	v_max_f32_e32 v106, 0, v111
	v_max_f32_e32 v107, 0, v107
	v_pk_mul_f32 v[96:97], v[96:97], v[114:115] op_sel_hi:[1,0]
	v_mul_f32_e32 v108, v108, v108
	v_mul_f32_e32 v105, v105, v105
	v_mul_f32_e32 v106, v106, v106
	v_mul_f32_e32 v107, v107, v107
	v_cvt_pk_bf16_f32 v104, v108, v104
	v_pk_mul_f32 v[100:101], v[100:101], v[114:115] op_sel_hi:[1,0]
	v_pk_mul_f32 v[98:99], v[98:99], v[114:115] op_sel_hi:[1,0]
	v_max_f32_e32 v96, 0, v96
	v_cvt_pk_bf16_f32 v105, v105, v106
	v_cvt_pk_bf16_f32 v106, v115, v109
	v_cvt_pk_bf16_f32 v107, v110, v107
	ds_bpermute_b32 v220, v228, v104
	ds_bpermute_b32 v221, v228, v105
	ds_bpermute_b32 v222, v228, v106
	ds_bpermute_b32 v223, v228, v107
	v_pk_mul_f32 v[102:103], v[102:103], v[114:115] op_sel_hi:[1,0]
	v_max_f32_e32 v97, 0, v97
	v_mul_f32_e32 v104, v96, v96
	v_max_f32_e32 v96, 0, v101
	v_max_f32_e32 v98, 0, v98
	v_max_f32_e32 v100, 0, v100
	v_mul_f32_e32 v96, v96, v96
	v_mul_f32_e32 v101, v97, v97
	v_max_f32_e32 v97, 0, v102
	v_mul_f32_e32 v102, v98, v98
	v_max_f32_e32 v98, 0, v103
	v_max_f32_e32 v99, 0, v99
	v_mul_f32_e32 v100, v100, v100
	v_mul_f32_e32 v97, v97, v97
	v_mul_f32_e32 v98, v98, v98
	v_mul_f32_e32 v99, v99, v99
	v_cvt_pk_bf16_f32 v96, v100, v96
	v_cvt_pk_bf16_f32 v97, v97, v98
	v_cvt_pk_bf16_f32 v98, v104, v101
	v_cvt_pk_bf16_f32 v99, v102, v99
	ds_bpermute_b32 v224, v228, v96
	ds_bpermute_b32 v225, v228, v97
	ds_bpermute_b32 v226, v228, v98
	ds_bpermute_b32 v227, v228, v99
	s_waitcnt lgkmcnt(4)
	global_store_dwordx4 v[112:113], v[220:223], off
	s_waitcnt lgkmcnt(0)
; __device__ __forceinline__ unsigned cvt_pk_bf16(float lo, float hi) { unsigned r; asm volatile("v_cvt_pk_bf16_f32 %0, %1, %2" : "=v"(r) : "v"(lo), "v"(hi)); return r; }
;     __device__ __forceinline__ void operator()(const f32x4 (&acc)[2][2][4][2], const Unit& u, int wr, int wc, int fr, int fq) const {
;     ...
;                 const int row = row0 + ai * HALF + m * 16;
;                 const f32x4* sp = (const f32x4*)(ss + (size_t)row * 16);
;                 const f32x4 a0 = sp[0], a1 = sp[1], a2 = sp[2], a3 = sp[3];
;                 const float tot = ((a0.x + a0.y) + (a0.z + a0.w)) + ((a1.x + a1.y) + (a1.z + a1.w)) + ((a2.x + a2.y) + (a2.z + a2.w)) + ((a3.x + a3.y) + (a3.z + a3.w));
;                 const float rs = rsqrtf(tot * (1.0f / 1024.0f) + 1e-6f);
;                 bf16_t* rowp = O + (size_t)row * ldc + col0;
; #pragma unroll
;                 for (int bj = 0; bj < 2; ++bj) {
;                     f32x4 v0 = acc[ai][bj][m][0] * rs, v1 = acc[ai][bj][m][1] * rs;
;                     if (ACT == 1) {
; #pragma unroll
;                         for (int e = 0; e < 4; ++e) { float a = fmaxf(v0[e], 0.f); v0[e] = a * a; float b = fmaxf(v1[e], 0.f); v1[e] = b * b; }
;                     }
;                     u32x4 w; w.x = cvt_pk_bf16(v0[0], v0[1]); w.y = cvt_pk_bf16(v0[2], v0[3]); w.z = cvt_pk_bf16(v1[0], v1[1]); w.w = cvt_pk_bf16(v1[2], v1[3]);
;                     *(u32x4*)(rowp + bj * HALF) = w;
	global_store_dwordx4 v[112:113], v[224:227], off offset:256
	s_nop 1
	v_or_b32_e32 v96, 32, v152
	v_ashrrev_i32_e32 v97, 31, v96
	v_lshlrev_b64 v[96:97], 13, v[96:97]
	v_lshl_add_u64 v[96:97], s[78:79], 0, v[96:97]
	v_lshl_add_u64 v[96:97], v[96:97], 0, v[150:151]
	v_mov_b32_e32 v98, v188
	v_pk_mul_f32 v[88:89], v[88:89], v[98:99] op_sel_hi:[1,0]
	v_pk_mul_f32 v[92:93], v[92:93], v[98:99] op_sel_hi:[1,0]
	v_pk_mul_f32 v[90:91], v[90:91], v[98:99] op_sel_hi:[1,0]
	v_max_f32_e32 v88, 0, v88
	v_pk_mul_f32 v[94:95], v[94:95], v[98:99] op_sel_hi:[1,0]
	v_mul_f32_e32 v99, v88, v88
	v_max_f32_e32 v88, 0, v93
	v_max_f32_e32 v89, 0, v89
	v_max_f32_e32 v90, 0, v90
	v_max_f32_e32 v92, 0, v92
	v_mul_f32_e32 v88, v88, v88
	v_mul_f32_e32 v93, v89, v89
	v_max_f32_e32 v89, 0, v94
	v_mul_f32_e32 v94, v90, v90
	v_max_f32_e32 v90, 0, v95
	v_max_f32_e32 v91, 0, v91
	v_pk_mul_f32 v[80:81], v[80:81], v[98:99] op_sel_hi:[1,0]
	v_mul_f32_e32 v92, v92, v92
	v_mul_f32_e32 v89, v89, v89
	v_mul_f32_e32 v90, v90, v90
	v_mul_f32_e32 v91, v91, v91
	v_cvt_pk_bf16_f32 v88, v92, v88
	v_pk_mul_f32 v[84:85], v[84:85], v[98:99] op_sel_hi:[1,0]
	v_pk_mul_f32 v[82:83], v[82:83], v[98:99] op_sel_hi:[1,0]
	v_max_f32_e32 v80, 0, v80
	v_cvt_pk_bf16_f32 v89, v89, v90
	v_cvt_pk_bf16_f32 v90, v99, v93
	v_cvt_pk_bf16_f32 v91, v94, v91
	ds_bpermute_b32 v220, v228, v88
	ds_bpermute_b32 v221, v228, v89
	ds_bpermute_b32 v222, v228, v90
	ds_bpermute_b32 v223, v228, v91
	v_pk_mul_f32 v[86:87], v[86:87], v[98:99] op_sel_hi:[1,0]
	v_max_f32_e32 v81, 0, v81
	v_mul_f32_e32 v88, v80, v80
	v_max_f32_e32 v80, 0, v85
	v_max_f32_e32 v82, 0, v82
	v_max_f32_e32 v84, 0, v84
	v_mul_f32_e32 v80, v80, v80
	v_mul_f32_e32 v85, v81, v81
	v_max_f32_e32 v81, 0, v86
	v_mul_f32_e32 v86, v82, v82
	v_max_f32_e32 v82, 0, v87
	v_max_f32_e32 v83, 0, v83
	v_mul_f32_e32 v84, v84, v84
	v_mul_f32_e32 v81, v81, v81
	v_mul_f32_e32 v82, v82, v82
	v_mul_f32_e32 v83, v83, v83
	v_cvt_pk_bf16_f32 v80, v84, v80
	v_cvt_pk_bf16_f32 v81, v81, v82
	v_cvt_pk_bf16_f32 v82, v88, v85
	v_cvt_pk_bf16_f32 v83, v86, v83
	ds_bpermute_b32 v224, v228, v80
	ds_bpermute_b32 v225, v228, v81
	ds_bpermute_b32 v226, v228, v82
	ds_bpermute_b32 v227, v228, v83
	s_waitcnt lgkmcnt(4)
	global_store_dwordx4 v[96:97], v[220:223], off
	s_waitcnt lgkmcnt(0)
	global_store_dwordx4 v[96:97], v[224:227], off offset:256
	s_nop 1
	v_or_b32_e32 v80, 48, v152
	v_ashrrev_i32_e32 v81, 31, v80
	v_lshlrev_b64 v[80:81], 13, v[80:81]
	v_lshl_add_u64 v[80:81], s[78:79], 0, v[80:81]
	v_lshl_add_u64 v[80:81], v[80:81], 0, v[150:151]
	v_mov_b32_e32 v82, v192
	v_pk_mul_f32 v[72:73], v[72:73], v[82:83] op_sel_hi:[1,0]
	v_pk_mul_f32 v[76:77], v[76:77], v[82:83] op_sel_hi:[1,0]
	v_pk_mul_f32 v[74:75], v[74:75], v[82:83] op_sel_hi:[1,0]
	v_max_f32_e32 v72, 0, v72
	v_pk_mul_f32 v[78:79], v[78:79], v[82:83] op_sel_hi:[1,0]
	v_mul_f32_e32 v83, v72, v72
	v_max_f32_e32 v72, 0, v77
	v_max_f32_e32 v73, 0, v73
	v_max_f32_e32 v74, 0, v74
	v_max_f32_e32 v76, 0, v76
	v_mul_f32_e32 v72, v72, v72
	v_mul_f32_e32 v77, v73, v73
	v_max_f32_e32 v73, 0, v78
	v_mul_f32_e32 v78, v74, v74
	v_max_f32_e32 v74, 0, v79
	v_max_f32_e32 v75, 0, v75
	v_pk_mul_f32 v[64:65], v[64:65], v[82:83] op_sel_hi:[1,0]
	v_mul_f32_e32 v76, v76, v76
	v_mul_f32_e32 v73, v73, v73
	v_mul_f32_e32 v74, v74, v74
	v_mul_f32_e32 v75, v75, v75
	v_cvt_pk_bf16_f32 v72, v76, v72
	v_pk_mul_f32 v[68:69], v[68:69], v[82:83] op_sel_hi:[1,0]
	v_pk_mul_f32 v[66:67], v[66:67], v[82:83] op_sel_hi:[1,0]
	v_max_f32_e32 v64, 0, v64
	v_cvt_pk_bf16_f32 v73, v73, v74
	v_cvt_pk_bf16_f32 v74, v83, v77
	v_cvt_pk_bf16_f32 v75, v78, v75
	ds_bpermute_b32 v220, v228, v72
	ds_bpermute_b32 v221, v228, v73
	ds_bpermute_b32 v222, v228, v74
	ds_bpermute_b32 v223, v228, v75
	v_pk_mul_f32 v[70:71], v[70:71], v[82:83] op_sel_hi:[1,0]
	v_max_f32_e32 v65, 0, v65
	v_mul_f32_e32 v72, v64, v64
	v_max_f32_e32 v64, 0, v69
	v_max_f32_e32 v66, 0, v66
	v_max_f32_e32 v68, 0, v68
	v_mul_f32_e32 v64, v64, v64
	v_mul_f32_e32 v69, v65, v65
	v_max_f32_e32 v65, 0, v70
	v_mul_f32_e32 v70, v66, v66
	v_max_f32_e32 v66, 0, v71
	v_max_f32_e32 v67, 0, v67
	v_mul_f32_e32 v68, v68, v68
	v_mul_f32_e32 v65, v65, v65
	v_mul_f32_e32 v66, v66, v66
	v_mul_f32_e32 v67, v67, v67
	v_cvt_pk_bf16_f32 v64, v68, v64
	v_cvt_pk_bf16_f32 v65, v65, v66
	v_cvt_pk_bf16_f32 v66, v72, v69
	v_cvt_pk_bf16_f32 v67, v70, v67
	ds_bpermute_b32 v224, v228, v64
	ds_bpermute_b32 v225, v228, v65
	ds_bpermute_b32 v226, v228, v66
	ds_bpermute_b32 v227, v228, v67
	s_waitcnt lgkmcnt(4)
	global_store_dwordx4 v[80:81], v[220:223], off
	s_waitcnt lgkmcnt(0)
; __device__ __forceinline__ unsigned cvt_pk_bf16(float lo, float hi) { unsigned r; asm volatile("v_cvt_pk_bf16_f32 %0, %1, %2" : "=v"(r) : "v"(lo), "v"(hi)); return r; }
;     __device__ __forceinline__ void operator()(const f32x4 (&acc)[2][2][4][2], const Unit& u, int wr, int wc, int fr, int fq) const {
;     ...
;                 const int row = row0 + ai * HALF + m * 16;
;                 const f32x4* sp = (const f32x4*)(ss + (size_t)row * 16);
;                 const f32x4 a0 = sp[0], a1 = sp[1], a2 = sp[2], a3 = sp[3];
;                 const float tot = ((a0.x + a0.y) + (a0.z + a0.w)) + ((a1.x + a1.y) + (a1.z + a1.w)) + ((a2.x + a2.y) + (a2.z + a2.w)) + ((a3.x + a3.y) + (a3.z + a3.w));
;                 const float rs = rsqrtf(tot * (1.0f / 1024.0f) + 1e-6f);
;                 bf16_t* rowp = O + (size_t)row * ldc + col0;
; #pragma unroll
;                 for (int bj = 0; bj < 2; ++bj) {
;                     f32x4 v0 = acc[ai][bj][m][0] * rs, v1 = acc[ai][bj][m][1] * rs;
;                     if (ACT == 1) {
; #pragma unroll
;                         for (int e = 0; e < 4; ++e) { float a = fmaxf(v0[e], 0.f); v0[e] = a * a; float b = fmaxf(v1[e], 0.f); v1[e] = b * b; }
;                     }
;                     u32x4 w; w.x = cvt_pk_bf16(v0[0], v0[1]); w.y = cvt_pk_bf16(v0[2], v0[3]); w.z = cvt_pk_bf16(v1[0], v1[1]); w.w = cvt_pk_bf16(v1[2], v1[3]);
;                     *(u32x4*)(rowp + bj * HALF) = w;
	global_store_dwordx4 v[80:81], v[224:227], off offset:256
	s_nop 1
	v_add_u32_e32 v64, 0x80, v152
	v_ashrrev_i32_e32 v65, 31, v64
	v_lshlrev_b64 v[64:65], 13, v[64:65]
	v_lshl_add_u64 v[64:65], s[78:79], 0, v[64:65]
	v_lshl_add_u64 v[64:65], v[64:65], 0, v[150:151]
	v_mov_b32_e32 v66, v196
	v_pk_mul_f32 v[56:57], v[56:57], v[66:67] op_sel_hi:[1,0]
	v_pk_mul_f32 v[60:61], v[60:61], v[66:67] op_sel_hi:[1,0]
	v_pk_mul_f32 v[58:59], v[58:59], v[66:67] op_sel_hi:[1,0]
	v_max_f32_e32 v56, 0, v56
	v_pk_mul_f32 v[62:63], v[62:63], v[66:67] op_sel_hi:[1,0]
	v_mul_f32_e32 v67, v56, v56
	v_max_f32_e32 v56, 0, v61
	v_max_f32_e32 v57, 0, v57
	v_max_f32_e32 v58, 0, v58
	v_max_f32_e32 v60, 0, v60
	v_mul_f32_e32 v56, v56, v56
	v_mul_f32_e32 v61, v57, v57
	v_max_f32_e32 v57, 0, v62
	v_mul_f32_e32 v62, v58, v58
	v_max_f32_e32 v58, 0, v63
	v_max_f32_e32 v59, 0, v59
	v_pk_mul_f32 v[48:49], v[48:49], v[66:67] op_sel_hi:[1,0]
	v_mul_f32_e32 v60, v60, v60
	v_mul_f32_e32 v57, v57, v57
	v_mul_f32_e32 v58, v58, v58
	v_mul_f32_e32 v59, v59, v59
	v_cvt_pk_bf16_f32 v56, v60, v56
	v_pk_mul_f32 v[52:53], v[52:53], v[66:67] op_sel_hi:[1,0]
	v_pk_mul_f32 v[50:51], v[50:51], v[66:67] op_sel_hi:[1,0]
	v_max_f32_e32 v48, 0, v48
	v_cvt_pk_bf16_f32 v57, v57, v58
	v_cvt_pk_bf16_f32 v58, v67, v61
	v_cvt_pk_bf16_f32 v59, v62, v59
	ds_bpermute_b32 v220, v228, v56
	ds_bpermute_b32 v221, v228, v57
	ds_bpermute_b32 v222, v228, v58
	ds_bpermute_b32 v223, v228, v59
	v_pk_mul_f32 v[54:55], v[54:55], v[66:67] op_sel_hi:[1,0]
	v_max_f32_e32 v49, 0, v49
	v_mul_f32_e32 v56, v48, v48
	v_max_f32_e32 v48, 0, v53
	v_max_f32_e32 v50, 0, v50
	v_max_f32_e32 v52, 0, v52
	v_mul_f32_e32 v48, v48, v48
	v_mul_f32_e32 v53, v49, v49
	v_max_f32_e32 v49, 0, v54
	v_mul_f32_e32 v54, v50, v50
	v_max_f32_e32 v50, 0, v55
	v_max_f32_e32 v51, 0, v51
	v_mul_f32_e32 v52, v52, v52
	v_mul_f32_e32 v49, v49, v49
	v_mul_f32_e32 v50, v50, v50
	v_mul_f32_e32 v51, v51, v51
	v_cvt_pk_bf16_f32 v48, v52, v48
	v_cvt_pk_bf16_f32 v49, v49, v50
	v_cvt_pk_bf16_f32 v50, v56, v53
	v_cvt_pk_bf16_f32 v51, v54, v51
	ds_bpermute_b32 v224, v228, v48
	ds_bpermute_b32 v225, v228, v49
	ds_bpermute_b32 v226, v228, v50
	ds_bpermute_b32 v227, v228, v51
	s_waitcnt lgkmcnt(4)
	global_store_dwordx4 v[64:65], v[220:223], off
	s_waitcnt lgkmcnt(0)
	global_store_dwordx4 v[64:65], v[224:227], off offset:256
	s_nop 1
	v_add_u32_e32 v48, 0x90, v152
	v_ashrrev_i32_e32 v49, 31, v48
	v_lshlrev_b64 v[48:49], 13, v[48:49]
	v_lshl_add_u64 v[48:49], s[78:79], 0, v[48:49]
	v_lshl_add_u64 v[48:49], v[48:49], 0, v[150:151]
	v_mov_b32_e32 v50, v208
	v_pk_mul_f32 v[40:41], v[40:41], v[50:51] op_sel_hi:[1,0]
	v_pk_mul_f32 v[44:45], v[44:45], v[50:51] op_sel_hi:[1,0]
	v_pk_mul_f32 v[42:43], v[42:43], v[50:51] op_sel_hi:[1,0]
	v_max_f32_e32 v40, 0, v40
	v_pk_mul_f32 v[46:47], v[46:47], v[50:51] op_sel_hi:[1,0]
	v_mul_f32_e32 v51, v40, v40
	v_max_f32_e32 v40, 0, v45
	v_max_f32_e32 v41, 0, v41
	v_max_f32_e32 v42, 0, v42
	v_max_f32_e32 v44, 0, v44
	v_mul_f32_e32 v40, v40, v40
	v_mul_f32_e32 v45, v41, v41
	v_max_f32_e32 v41, 0, v46
	v_mul_f32_e32 v46, v42, v42
	v_max_f32_e32 v42, 0, v47
	v_max_f32_e32 v43, 0, v43
	v_pk_mul_f32 v[32:33], v[32:33], v[50:51] op_sel_hi:[1,0]
	v_mul_f32_e32 v44, v44, v44
	v_mul_f32_e32 v41, v41, v41
	v_mul_f32_e32 v42, v42, v42
	v_mul_f32_e32 v43, v43, v43
	v_cvt_pk_bf16_f32 v40, v44, v40
	v_pk_mul_f32 v[36:37], v[36:37], v[50:51] op_sel_hi:[1,0]
	v_pk_mul_f32 v[34:35], v[34:35], v[50:51] op_sel_hi:[1,0]
	v_max_f32_e32 v32, 0, v32
	v_cvt_pk_bf16_f32 v41, v41, v42
	v_cvt_pk_bf16_f32 v42, v51, v45
	v_cvt_pk_bf16_f32 v43, v46, v43
	ds_bpermute_b32 v220, v228, v40
	ds_bpermute_b32 v221, v228, v41
	ds_bpermute_b32 v222, v228, v42
	ds_bpermute_b32 v223, v228, v43
	v_pk_mul_f32 v[38:39], v[38:39], v[50:51] op_sel_hi:[1,0]
	v_max_f32_e32 v33, 0, v33
	v_mul_f32_e32 v40, v32, v32
	v_max_f32_e32 v32, 0, v37
	v_max_f32_e32 v34, 0, v34
	v_max_f32_e32 v36, 0, v36
	v_mul_f32_e32 v32, v32, v32
	v_mul_f32_e32 v37, v33, v33
	v_max_f32_e32 v33, 0, v38
	v_mul_f32_e32 v38, v34, v34
	v_max_f32_e32 v34, 0, v39
	v_max_f32_e32 v35, 0, v35
	v_mul_f32_e32 v36, v36, v36
	v_mul_f32_e32 v33, v33, v33
	v_mul_f32_e32 v34, v34, v34
	v_mul_f32_e32 v35, v35, v35
	v_cvt_pk_bf16_f32 v32, v36, v32
	v_cvt_pk_bf16_f32 v33, v33, v34
	v_cvt_pk_bf16_f32 v34, v40, v37
	v_cvt_pk_bf16_f32 v35, v38, v35
	ds_bpermute_b32 v224, v228, v32
	ds_bpermute_b32 v225, v228, v33
	ds_bpermute_b32 v226, v228, v34
	ds_bpermute_b32 v227, v228, v35
	s_waitcnt lgkmcnt(4)
	global_store_dwordx4 v[48:49], v[220:223], off
	s_waitcnt lgkmcnt(0)
; __device__ __forceinline__ unsigned cvt_pk_bf16(float lo, float hi) { unsigned r; asm volatile("v_cvt_pk_bf16_f32 %0, %1, %2" : "=v"(r) : "v"(lo), "v"(hi)); return r; }
;     __device__ __forceinline__ void operator()(const f32x4 (&acc)[2][2][4][2], const Unit& u, int wr, int wc, int fr, int fq) const {
;     ...
;                 const int row = row0 + ai * HALF + m * 16;
;                 const f32x4* sp = (const f32x4*)(ss + (size_t)row * 16);
;                 const f32x4 a0 = sp[0], a1 = sp[1], a2 = sp[2], a3 = sp[3];
;                 const float tot = ((a0.x + a0.y) + (a0.z + a0.w)) + ((a1.x + a1.y) + (a1.z + a1.w)) + ((a2.x + a2.y) + (a2.z + a2.w)) + ((a3.x + a3.y) + (a3.z + a3.w));
;                 const float rs = rsqrtf(tot * (1.0f / 1024.0f) + 1e-6f);
;                 bf16_t* rowp = O + (size_t)row * ldc + col0;
; #pragma unroll
;                 for (int bj = 0; bj < 2; ++bj) {
;                     f32x4 v0 = acc[ai][bj][m][0] * rs, v1 = acc[ai][bj][m][1] * rs;
;                     if (ACT == 1) {
; #pragma unroll
;                         for (int e = 0; e < 4; ++e) { float a = fmaxf(v0[e], 0.f); v0[e] = a * a; float b = fmaxf(v1[e], 0.f); v1[e] = b * b; }
;                     }
;                     u32x4 w; w.x = cvt_pk_bf16(v0[0], v0[1]); w.y = cvt_pk_bf16(v0[2], v0[3]); w.z = cvt_pk_bf16(v1[0], v1[1]); w.w = cvt_pk_bf16(v1[2], v1[3]);
;                     *(u32x4*)(rowp + bj * HALF) = w;
	global_store_dwordx4 v[48:49], v[224:227], off offset:256
	s_nop 1
	v_add_u32_e32 v32, 0xa0, v152
	v_ashrrev_i32_e32 v33, 31, v32
	v_lshlrev_b64 v[32:33], 13, v[32:33]
	v_lshl_add_u64 v[32:33], s[78:79], 0, v[32:33]
	v_lshl_add_u64 v[32:33], v[32:33], 0, v[150:151]
	v_mov_b32_e32 v34, v212
	v_pk_mul_f32 v[24:25], v[24:25], v[34:35] op_sel_hi:[1,0]
	v_pk_mul_f32 v[28:29], v[28:29], v[34:35] op_sel_hi:[1,0]
	v_pk_mul_f32 v[26:27], v[26:27], v[34:35] op_sel_hi:[1,0]
	v_max_f32_e32 v24, 0, v24
	v_pk_mul_f32 v[30:31], v[30:31], v[34:35] op_sel_hi:[1,0]
	v_mul_f32_e32 v35, v24, v24
	v_max_f32_e32 v24, 0, v29
	v_max_f32_e32 v25, 0, v25
	v_max_f32_e32 v26, 0, v26
	v_max_f32_e32 v28, 0, v28
	v_mul_f32_e32 v24, v24, v24
	v_mul_f32_e32 v29, v25, v25
	v_max_f32_e32 v25, 0, v30
	v_mul_f32_e32 v30, v26, v26
	v_max_f32_e32 v26, 0, v31
	v_max_f32_e32 v27, 0, v27
	v_pk_mul_f32 v[16:17], v[16:17], v[34:35] op_sel_hi:[1,0]
	v_mul_f32_e32 v28, v28, v28
	v_mul_f32_e32 v25, v25, v25
	v_mul_f32_e32 v26, v26, v26
	v_mul_f32_e32 v27, v27, v27
	v_cvt_pk_bf16_f32 v24, v28, v24
	v_pk_mul_f32 v[20:21], v[20:21], v[34:35] op_sel_hi:[1,0]
	v_pk_mul_f32 v[18:19], v[18:19], v[34:35] op_sel_hi:[1,0]
	v_max_f32_e32 v16, 0, v16
	v_cvt_pk_bf16_f32 v25, v25, v26
	v_cvt_pk_bf16_f32 v26, v35, v29
	v_cvt_pk_bf16_f32 v27, v30, v27
	ds_bpermute_b32 v220, v228, v24
	ds_bpermute_b32 v221, v228, v25
	ds_bpermute_b32 v222, v228, v26
	ds_bpermute_b32 v223, v228, v27
	v_pk_mul_f32 v[22:23], v[22:23], v[34:35] op_sel_hi:[1,0]
	v_max_f32_e32 v17, 0, v17
	v_mul_f32_e32 v24, v16, v16
	v_max_f32_e32 v16, 0, v21
	v_max_f32_e32 v18, 0, v18
	v_max_f32_e32 v20, 0, v20
	v_mul_f32_e32 v16, v16, v16
	v_mul_f32_e32 v21, v17, v17
	v_max_f32_e32 v17, 0, v22
	v_mul_f32_e32 v22, v18, v18
	v_max_f32_e32 v18, 0, v23
	v_max_f32_e32 v19, 0, v19
	v_mul_f32_e32 v20, v20, v20
	v_mul_f32_e32 v17, v17, v17
	v_mul_f32_e32 v18, v18, v18
	v_mul_f32_e32 v19, v19, v19
	v_cvt_pk_bf16_f32 v16, v20, v16
	v_cvt_pk_bf16_f32 v17, v17, v18
	v_cvt_pk_bf16_f32 v18, v24, v21
	v_cvt_pk_bf16_f32 v19, v22, v19
	ds_bpermute_b32 v224, v228, v16
	ds_bpermute_b32 v225, v228, v17
	ds_bpermute_b32 v226, v228, v18
	ds_bpermute_b32 v227, v228, v19
	s_waitcnt lgkmcnt(4)
	global_store_dwordx4 v[32:33], v[220:223], off
	s_waitcnt lgkmcnt(0)
	global_store_dwordx4 v[32:33], v[224:227], off offset:256
	s_nop 1
	v_add_u32_e32 v16, 0xb0, v152
	v_ashrrev_i32_e32 v17, 31, v16
	v_lshlrev_b64 v[16:17], 13, v[16:17]
	v_lshl_add_u64 v[16:17], s[78:79], 0, v[16:17]
	v_lshl_add_u64 v[16:17], v[16:17], 0, v[150:151]
	v_mov_b32_e32 v18, v216
	v_pk_mul_f32 v[8:9], v[8:9], v[18:19] op_sel_hi:[1,0]
	v_pk_mul_f32 v[12:13], v[12:13], v[18:19] op_sel_hi:[1,0]
	v_pk_mul_f32 v[10:11], v[10:11], v[18:19] op_sel_hi:[1,0]
	v_max_f32_e32 v8, 0, v8
	v_pk_mul_f32 v[14:15], v[14:15], v[18:19] op_sel_hi:[1,0]
	v_mul_f32_e32 v19, v8, v8
	v_max_f32_e32 v8, 0, v13
	v_max_f32_e32 v9, 0, v9
	v_max_f32_e32 v10, 0, v10
	v_max_f32_e32 v12, 0, v12
	v_mul_f32_e32 v8, v8, v8
	v_mul_f32_e32 v13, v9, v9
	v_max_f32_e32 v9, 0, v14
	v_mul_f32_e32 v14, v10, v10
	v_max_f32_e32 v10, 0, v15
	v_max_f32_e32 v11, 0, v11
	v_pk_mul_f32 v[2:3], v[2:3], v[18:19] op_sel_hi:[1,0]
	v_pk_mul_f32 v[0:1], v[0:1], v[18:19] op_sel_hi:[1,0]
	v_mul_f32_e32 v12, v12, v12
	v_mul_f32_e32 v9, v9, v9
	v_mul_f32_e32 v10, v10, v10
	v_mul_f32_e32 v11, v11, v11
	v_cvt_pk_bf16_f32 v8, v12, v8
	v_pk_mul_f32 v[6:7], v[6:7], v[18:19] op_sel_hi:[1,0]
	v_pk_mul_f32 v[4:5], v[4:5], v[18:19] op_sel_hi:[1,0]
	v_max_f32_e32 v0, 0, v0
	v_max_f32_e32 v1, 0, v1
	v_max_f32_e32 v2, 0, v2
	v_cvt_pk_bf16_f32 v9, v9, v10
	v_cvt_pk_bf16_f32 v10, v19, v13
	v_cvt_pk_bf16_f32 v11, v14, v11
	ds_bpermute_b32 v220, v228, v8
	ds_bpermute_b32 v221, v228, v9
	ds_bpermute_b32 v222, v228, v10
	ds_bpermute_b32 v223, v228, v11
	v_max_f32_e32 v3, 0, v3
	v_max_f32_e32 v4, 0, v4
	v_mul_f32_e32 v8, v0, v0
	v_max_f32_e32 v0, 0, v5
	v_mul_f32_e32 v5, v1, v1
	v_max_f32_e32 v1, 0, v6
	v_mul_f32_e32 v6, v2, v2
	v_max_f32_e32 v2, 0, v7
	v_mul_f32_e32 v0, v0, v0
	v_mul_f32_e32 v1, v1, v1
	v_mul_f32_e32 v2, v2, v2
	v_mul_f32_e32 v3, v3, v3
	s_andn2_b64 vcc, exec, s[38:39]
	v_mul_f32_e32 v4, v4, v4
	v_cvt_pk_bf16_f32 v0, v4, v0
	v_cvt_pk_bf16_f32 v1, v1, v2
	v_cvt_pk_bf16_f32 v2, v8, v5
	v_cvt_pk_bf16_f32 v3, v6, v3
	ds_bpermute_b32 v224, v228, v0
	ds_bpermute_b32 v225, v228, v1
	ds_bpermute_b32 v226, v228, v2
	ds_bpermute_b32 v227, v228, v3
	s_waitcnt lgkmcnt(4)
	global_store_dwordx4 v[16:17], v[220:223], off
	s_waitcnt lgkmcnt(0)
	global_store_dwordx4 v[16:17], v[224:227], off offset:256
	s_cbranch_vccnz .LBB0_1144
	s_andn2_b64 vcc, exec, s[0:1]
	s_cbranch_vccnz .LBB0_1143
	s_barrier
	s_branch .LBB0_1143
